# g1 conv loads batched, residual epilogue loads batched, sample-attn loads hoisted
# speedup vs baseline: 1.1157x; 1.0600x over previous
; __device__ __forceinline__ unsigned pk2(float lo, float hi) { const f32x2_ v = {lo, hi}; return __builtin_bit_cast(unsigned, __builtin_convertvector(v, bf16x2_)); }
; __device__ __forceinline__ void attn_sample_unit(const PP P, LAS unsigned char* lds, int b, int h) {
;     ...
;     for (int kb = kb0; kb < kb1; ++kb) {
;         f32x4 s[2]; int kof[2];
; #pragma unroll
;         for (int sub = 0; sub < 2; ++sub) { const int key0 = kb * 32 + sub * 16; const bool valid = key0 < nkeys; kof[sub] = (valid && key0 >= 2048) ? 65536 + b * 16 + (key0 - 2048) : b * 2048 + (valid ? key0 : 0);
;             const size_t kr = (size_t)keybase + kof[sub] + fr;
;             const bf16x8 a0 = *(const bf16x8*)(KN + kr * 512 + h * 64 + fq * 8), a1 = *(const bf16x8*)(KN + kr * 512 + h * 64 + 32 + fq * 8), a2 = *(const bf16x8*)(KPEB + kr * 32 + fq * 8);
;             f32x4 acc = {0.f, 0.f, 0.f, 0.f}; acc = mfma16(a0, Qb[0], acc); acc = mfma16(a1, Qb[1], acc); acc = mfma16(a2, Qb[2], acc);
;             if (!valid) acc = (f32x4){-INFINITY, -INFINITY, -INFINITY, -INFINITY};
;             s[sub] = acc; }
;         float mx = fmaxf(fmaxf(fmaxf(s[0][0], s[0][1]), fmaxf(s[0][2], s[0][3])), fmaxf(fmaxf(s[1][0], s[1][1]), fmaxf(s[1][2], s[1][3])));
;         mx = fmaxf(mx, xor16_get(mx)); mx = xor32_max(mx);
;         const float mnew = fmaxf(m, mx); const float alpha = __builtin_amdgcn_exp2f(m - mnew); m = mnew;
;         float p[8]; float ps = 0.f;
; #pragma unroll
;         for (int j = 0; j < 4; ++j) { p[j] = __builtin_amdgcn_exp2f(s[0][j] - mnew); p[4 + j] = __builtin_amdgcn_exp2f(s[1][j] - mnew); ps += p[j] + p[4 + j]; }
;         lsum = lsum * alpha + ps;
;         u32x4 pw; pw.x = pk2(p[0], p[1]); pw.y = pk2(p[2], p[3]); pw.z = pk2(p[4], p[5]); pw.w = pk2(p[6], p[7]);
;         const bf16x8 Pb = __builtin_bit_cast(bf16x8, pw);
; #pragma unroll
;         for (int nt = 0; nt < 4; ++nt) { const bf16* vrow = VT + (size_t)(h * 64 + 16 * nt + fr) * NK + keybase + fq * 4;
;             const s16x4 a = *(const s16x4*)(vrow + kof[0]), c = *(const s16x4*)(vrow + kof[1]);
;             bf16x8 va; va[0] = a[0]; va[1] = a[1]; va[2] = a[2]; va[3] = a[3]; va[4] = c[0]; va[5] = c[1]; va[6] = c[2]; va[7] = c[3];
;             O[nt] = mfma16(va, Pb, O[nt] * alpha); }
.LBB0_54:
	v_add_u32_e32 v200, 16, v51
	v_cmp_gt_i32_e32 vcc, 0x810, v200
	v_cndmask_b32_e32 v200, 0, v200, vcc
	v_add_u32_e32 v228, s36, v200
	v_ashrrev_i32_e32 v229, 31, v228
	v_lshl_add_u64 v[230:231], v[228:229], 0, v[108:109]
	v_lshlrev_b64 v[232:233], 10, v[230:231]
	v_lshl_add_u64 v[232:233], v[48:49], 0, v[232:233]
	global_load_dwordx4 v[200:203], v[232:233], off
	global_load_dwordx4 v[204:207], v[232:233], off offset:64
	v_lshlrev_b64 v[230:231], 6, v[230:231]
	v_lshl_add_u64 v[230:231], v[110:111], 0, v[230:231]
	global_load_dwordx4 v[208:211], v[230:231], off
	v_lshlrev_b64 v[234:235], 1, v[228:229]
	s_movk_i32 s14, 0x41
	v_cmp_gt_i32_e32 vcc, s14, v59
	v_cmp_eq_u32_e64 s[14:15], 64, v59
	v_mov_b32_e32 v31, s35
	v_cndmask_b32_e32 v30, 0, v51, vcc
	v_add_u32_e32 v30, s36, v30
	v_cndmask_b32_e64 v60, v30, v31, s[14:15]
	v_ashrrev_i32_e32 v61, 31, v60
	v_lshl_add_u64 v[52:53], v[60:61], 0, v[108:109]
	v_lshlrev_b64 v[30:31], 10, v[52:53]
	v_lshl_add_u64 v[34:35], v[48:49], 0, v[30:31]
	global_load_dwordx4 v[30:33], v[34:35], off
	s_nop 0
	global_load_dwordx4 v[34:37], v[34:35], off offset:64
	v_lshlrev_b64 v[52:53], 6, v[52:53]
	v_lshl_add_u64 v[52:53], v[110:111], 0, v[52:53]
	global_load_dwordx4 v[52:55], v[52:53], off
	s_movk_i32 s14, 0x810
	v_mov_b32_e32 v62, v24
	v_mov_b32_e32 v24, v50
	v_lshlrev_b64 v[60:61], 1, v[60:61]
	v_lshl_add_u64 v[236:237], v[40:41], 0, v[60:61]
	global_load_dwordx2 v[212:213], v[236:237], off
	v_lshl_add_u64 v[238:239], v[40:41], 0, v[234:235]
	global_load_dwordx2 v[214:215], v[238:239], off
	v_lshl_add_u64 v[236:237], v[42:43], 0, v[60:61]
	global_load_dwordx2 v[216:217], v[236:237], off
	v_lshl_add_u64 v[238:239], v[42:43], 0, v[234:235]
	global_load_dwordx2 v[218:219], v[238:239], off
	v_lshl_add_u64 v[236:237], v[44:45], 0, v[60:61]
	global_load_dwordx2 v[220:221], v[236:237], off
	v_lshl_add_u64 v[238:239], v[44:45], 0, v[234:235]
	global_load_dwordx2 v[222:223], v[238:239], off
	v_lshl_add_u64 v[236:237], v[46:47], 0, v[60:61]
	global_load_dwordx2 v[224:225], v[236:237], off
	v_lshl_add_u64 v[238:239], v[46:47], 0, v[234:235]
	global_load_dwordx2 v[226:227], v[238:239], off
	s_waitcnt vmcnt(10)
	v_mfma_f32_16x16x32_bf16 v[30:33], v[30:33], v[26:29], 0
	s_waitcnt vmcnt(9)
	v_mfma_f32_16x16x32_bf16 v[30:33], v[34:37], v[20:23], v[30:33]
	s_waitcnt vmcnt(8)
	v_mfma_f32_16x16x32_bf16 v[30:33], v[52:55], v[16:19], v[30:33]
	s_nop 7
	v_cndmask_b32_e32 v58, v166, v30, vcc
	v_add_u32_e32 v30, 16, v51
	v_cndmask_b32_e32 v56, v166, v32, vcc
	v_cndmask_b32_e32 v57, v166, v33, vcc
	v_cndmask_b32_e32 v63, v166, v31, vcc
	v_cmp_gt_i32_e32 vcc, s14, v30
	v_max_f32_e32 v50, v56, v56
	v_add_u32_e32 v51, 32, v51
	v_cndmask_b32_e32 v30, 0, v30, vcc
	v_add_u32_e32 v36, s36, v30
	v_ashrrev_i32_e32 v37, 31, v36
	v_lshl_add_u64 v[34:35], v[36:37], 0, v[108:109]
	v_lshlrev_b64 v[30:31], 10, v[34:35]
	v_lshl_add_u64 v[52:53], v[48:49], 0, v[30:31]
	v_lshlrev_b64 v[34:35], 6, v[34:35]
	v_lshl_add_u64 v[34:35], v[110:111], 0, v[34:35]
	v_max_f32_e32 v34, v63, v63
	v_max_f32_e32 v35, v58, v58
	v_max_f32_e32 v34, v35, v34
	v_max_f32_e32 v35, v57, v57
	v_max_f32_e32 v35, v50, v35
	s_waitcnt vmcnt(8)
	v_mfma_f32_16x16x32_bf16 v[30:33], v[200:203], v[26:29], 0
	v_mfma_f32_16x16x32_bf16 v[30:33], v[204:207], v[20:23], v[30:33]
	v_mfma_f32_16x16x32_bf16 v[30:33], v[208:211], v[16:19], v[30:33]
	s_nop 7
	v_cndmask_b32_e32 v32, v166, v32, vcc
	v_cndmask_b32_e32 v33, v166, v33, vcc
	v_max_f32_e32 v50, v33, v33
	v_max_f32_e32 v52, v32, v32
	v_cndmask_b32_e32 v31, v166, v31, vcc
	v_cndmask_b32_e32 v30, v166, v30, vcc
	v_max_f32_e32 v50, v52, v50
	v_max3_f32 v50, v30, v31, v50
	v_max3_f32 v34, v34, v35, v50
	ds_swizzle_b32 v35, v34 offset:swizzle(SWAP,16)
	s_waitcnt lgkmcnt(0)
	v_max_f32_e32 v35, v35, v35
	v_max_f32_e32 v34, v34, v35
	v_mov_b32_e32 v35, v34
	s_nop 1
	v_permlane32_swap_b32_e32 v34, v35
	v_max3_f32 v50, v24, v34, v35
	v_sub_f32_e32 v34, v24, v50
	v_sub_f32_e32 v24, v58, v50
	v_exp_f32_e32 v35, v24
	v_sub_f32_e32 v24, v30, v50
	v_sub_f32_e32 v30, v31, v50
	v_exp_f32_e32 v64, v24
	v_sub_f32_e32 v24, v63, v50
	v_exp_f32_e32 v52, v30
	v_exp_f32_e32 v24, v24
	v_sub_f32_e32 v30, v56, v50
	v_exp_f32_e32 v31, v30
	v_sub_f32_e32 v30, v32, v50
	v_exp_f32_e32 v63, v30
	v_sub_f32_e32 v30, v57, v50
	v_add_f32_e32 v53, v64, v35
	v_exp_f32_e32 v56, v30
	v_sub_f32_e32 v30, v33, v50
	v_cvt_pk_bf16_f32 v32, v64, v52
	v_lshlrev_b64 v[64:65], 1, v[36:37]
	v_exp_f32_e32 v54, v30
	v_exp_f32_e32 v58, v34
	v_cvt_pk_bf16_f32 v30, v35, v24
	v_add_f32_e32 v55, v63, v31
	v_cvt_pk_bf16_f32 v31, v31, v56
	v_cvt_pk_bf16_f32 v33, v63, v54
	v_pk_mul_f32 v[14:15], v[14:15], v[58:59] op_sel_hi:[1,0]
	v_pk_mul_f32 v[12:13], v[12:13], v[58:59] op_sel_hi:[1,0]
	v_pk_mul_f32 v[10:11], v[10:11], v[58:59] op_sel_hi:[1,0]
	v_pk_mul_f32 v[8:9], v[8:9], v[58:59] op_sel_hi:[1,0]
	v_pk_mul_f32 v[6:7], v[6:7], v[58:59] op_sel_hi:[1,0]
	v_pk_mul_f32 v[4:5], v[4:5], v[58:59] op_sel_hi:[1,0]
	v_pk_mul_f32 v[2:3], v[2:3], v[58:59] op_sel_hi:[1,0]
	v_pk_mul_f32 v[0:1], v[0:1], v[58:59] op_sel_hi:[1,0]
	v_add_u32_e32 v59, 1, v59
	v_cmp_ge_i32_e32 vcc, v59, v149
	s_or_b64 s[26:27], vcc, s[26:27]
	s_waitcnt vmcnt(6)
	v_mfma_f32_16x16x32_bf16 v[12:15], v[212:215], v[30:33], v[12:15]
	s_waitcnt vmcnt(4)
	v_mfma_f32_16x16x32_bf16 v[8:11], v[216:219], v[30:33], v[8:11]
	s_waitcnt vmcnt(2)
	v_mfma_f32_16x16x32_bf16 v[4:7], v[220:223], v[30:33], v[4:7]
	s_waitcnt vmcnt(0)
	v_mfma_f32_16x16x32_bf16 v[0:3], v[224:227], v[30:33], v[0:3]
	v_add_f32_e64 v30, v52, v24
	v_add_f32_e64 v31, v53, v25
	v_pk_add_f32 v[30:31], v[30:31], v[30:31] op_sel_hi:[0,1]
	v_mov_b32_e32 v57, v31
	v_pk_add_f32 v[30:31], v[54:55], v[56:57]
	s_nop 0
	v_add_f32_e32 v24, v30, v31
	v_fmac_f32_e32 v24, v62, v58
	s_andn2_b64 exec, exec, s[26:27]
	s_cbranch_execnz .LBB0_54
	s_or_b64 exec, exec, s[26:27]

; __device__ __forceinline__ float siluf_(float x) { return x * sigmoidf_(x); }
; __device__ __forceinline__ void g1_phase(const PP P, int l, LAS unsigned char* lds) {
;     ...
;                   for (int tb = 0; tb < 64; tb += 32) { float xv[32];
; #pragma unroll
;                     for (int i = 0; i < 32; ++i) { xv[i] = bf2f(*pr); pr += HLD; asm volatile("" : "+v"(pr)); }
; #pragma unroll
;                     for (int i = 0; i < 32; ++i) { const float y = w0 * x0 + w1 * x1 + w2 * x2 + w3 * xv[i]; dst[(tb + i) * 65] = siluf_(y); x0 = x1; x1 = x2; x2 = xv[i]; } }
.LBB0_501:
	v_cndmask_b32_e64 v4, 0, 1, s[94:95]
	v_cmp_ne_u32_e32 vcc, 1, v4
	s_mov_b64 s[94:95], 0
	s_and_b64 vcc, exec, vcc
	global_load_ushort v75, v[2:3], off
	v_lshl_add_u64 v[2:3], v[2:3], 0, s[82:83]
	global_load_ushort v74, v[2:3], off
	v_lshl_add_u64 v[2:3], v[2:3], 0, s[82:83]
	global_load_ushort v73, v[2:3], off
	v_lshl_add_u64 v[2:3], v[2:3], 0, s[82:83]
	global_load_ushort v72, v[2:3], off
	v_lshl_add_u64 v[2:3], v[2:3], 0, s[82:83]
	global_load_ushort v71, v[2:3], off
	v_lshl_add_u64 v[2:3], v[2:3], 0, s[82:83]
	global_load_ushort v70, v[2:3], off
	v_lshl_add_u64 v[2:3], v[2:3], 0, s[82:83]
	global_load_ushort v69, v[2:3], off
	v_lshl_add_u64 v[2:3], v[2:3], 0, s[82:83]
	global_load_ushort v63, v[2:3], off
	v_lshl_add_u64 v[2:3], v[2:3], 0, s[82:83]
	global_load_ushort v61, v[2:3], off
	v_lshl_add_u64 v[2:3], v[2:3], 0, s[82:83]
	global_load_ushort v59, v[2:3], off
	v_lshl_add_u64 v[2:3], v[2:3], 0, s[82:83]
	global_load_ushort v57, v[2:3], off
	v_lshl_add_u64 v[2:3], v[2:3], 0, s[82:83]
	global_load_ushort v55, v[2:3], off
	v_lshl_add_u64 v[2:3], v[2:3], 0, s[82:83]
	global_load_ushort v53, v[2:3], off
	v_lshl_add_u64 v[2:3], v[2:3], 0, s[82:83]
	global_load_ushort v51, v[2:3], off
	v_lshl_add_u64 v[2:3], v[2:3], 0, s[82:83]
	global_load_ushort v49, v[2:3], off
	v_lshl_add_u64 v[2:3], v[2:3], 0, s[82:83]
	global_load_ushort v47, v[2:3], off
	v_lshl_add_u64 v[2:3], v[2:3], 0, s[82:83]
	global_load_ushort v45, v[2:3], off
	v_lshl_add_u64 v[2:3], v[2:3], 0, s[82:83]
	global_load_ushort v43, v[2:3], off
	v_lshl_add_u64 v[2:3], v[2:3], 0, s[82:83]
	global_load_ushort v41, v[2:3], off
	v_lshl_add_u64 v[2:3], v[2:3], 0, s[82:83]
	global_load_ushort v39, v[2:3], off
	v_lshl_add_u64 v[2:3], v[2:3], 0, s[82:83]
	global_load_ushort v37, v[2:3], off
	v_lshl_add_u64 v[2:3], v[2:3], 0, s[82:83]
	global_load_ushort v35, v[2:3], off
	v_lshl_add_u64 v[2:3], v[2:3], 0, s[82:83]
	global_load_ushort v23, v[2:3], off
	v_lshl_add_u64 v[2:3], v[2:3], 0, s[82:83]
	global_load_ushort v22, v[2:3], off
	v_lshl_add_u64 v[2:3], v[2:3], 0, s[82:83]
	global_load_ushort v21, v[2:3], off
	v_lshl_add_u64 v[2:3], v[2:3], 0, s[82:83]
	global_load_ushort v20, v[2:3], off
	v_lshl_add_u64 v[2:3], v[2:3], 0, s[82:83]
	global_load_ushort v19, v[2:3], off
	v_lshl_add_u64 v[2:3], v[2:3], 0, s[82:83]
	global_load_ushort v7, v[2:3], off
	v_lshl_add_u64 v[2:3], v[2:3], 0, s[82:83]
	global_load_ushort v6, v[2:3], off
	v_lshl_add_u64 v[2:3], v[2:3], 0, s[82:83]
	v_lshl_add_u64 v[76:77], v[2:3], 0, s[82:83]
	global_load_ushort v4, v[2:3], off
	global_load_ushort v5, v[76:77], off
	v_lshl_add_u64 v[2:3], v[76:77], 0, s[82:83]
	global_load_ushort v11, v[2:3], off
	v_lshl_add_u64 v[2:3], v[2:3], 0, s[82:83]
	s_waitcnt vmcnt(0)
	v_lshlrev_b32_e32 v75, 16, v75
	v_lshlrev_b32_e32 v74, 16, v74
	v_lshlrev_b32_e32 v73, 16, v73
	v_lshlrev_b32_e32 v72, 16, v72
	v_lshlrev_b32_e32 v71, 16, v71
	v_lshlrev_b32_e32 v70, 16, v70
	v_lshlrev_b32_e32 v69, 16, v69
	v_lshlrev_b32_e32 v63, 16, v63
	v_lshlrev_b32_e32 v61, 16, v61
	v_lshlrev_b32_e32 v59, 16, v59
	v_lshlrev_b32_e32 v57, 16, v57
	v_lshlrev_b32_e32 v55, 16, v55
	v_lshlrev_b32_e32 v53, 16, v53
	v_lshlrev_b32_e32 v51, 16, v51
	v_lshlrev_b32_e32 v49, 16, v49
	v_lshlrev_b32_e32 v47, 16, v47
	v_lshlrev_b32_e32 v45, 16, v45
	v_lshlrev_b32_e32 v43, 16, v43
	v_lshlrev_b32_e32 v41, 16, v41
	v_lshlrev_b32_e32 v39, 16, v39
	v_lshlrev_b32_e32 v37, 16, v37
	v_lshlrev_b32_e32 v35, 16, v35
	v_lshlrev_b32_e32 v23, 16, v23
	v_lshlrev_b32_e32 v22, 16, v22
	v_lshlrev_b32_e32 v21, 16, v21
	v_lshlrev_b32_e32 v20, 16, v20
	v_lshlrev_b32_e32 v19, 16, v19
	v_lshlrev_b32_e32 v7, 16, v7
	v_lshlrev_b32_e32 v6, 16, v6
	v_lshlrev_b32_e32 v4, 16, v4
	v_lshlrev_b32_e32 v5, 16, v5
	v_lshlrev_b32_e32 v11, 16, v11
	v_mul_f32_e32 v76, v18, v9
	v_mul_f32_e32 v77, v18, v10
	v_fmac_f32_e32 v76, v15, v8
	v_fmac_f32_e32 v77, v15, v9
	v_fmac_f32_e32 v76, v16, v10
	v_fmac_f32_e32 v77, v16, v75
	v_fmac_f32_e32 v76, v17, v75
	v_fmac_f32_e32 v77, v17, v74
	v_mul_f32_e32 v8, 0xbfb8aa3b, v76
	v_mul_f32_e32 v9, 0xbfb8aa3b, v77
	v_exp_f32_e32 v8, v8
	v_exp_f32_e32 v9, v9
	s_nop 0
	v_add_f32_e32 v8, 1.0, v8
	v_add_f32_e32 v9, 1.0, v9
	v_rcp_f32_e32 v8, v8
	v_rcp_f32_e32 v9, v9
	s_nop 0
	v_mul_f32_e32 v8, v76, v8
	v_add_u32_e32 v76, s28, v64
	v_mul_f32_e32 v9, v77, v9
	ds_write2_b32 v76, v8, v9 offset1:65
	v_mul_f32_e32 v8, v18, v75
	v_fmac_f32_e32 v8, v15, v10
	v_fmac_f32_e32 v8, v16, v74
	v_fmac_f32_e32 v8, v17, v73
	v_mul_f32_e32 v9, 0xbfb8aa3b, v8
	v_exp_f32_e32 v9, v9
	s_movk_i32 s28, 0x2080
	v_add_f32_e32 v9, 1.0, v9
	v_rcp_f32_e32 v9, v9
	s_nop 0
	s_nop 0
	v_mul_f32_e32 v8, v8, v9
	v_mul_f32_e32 v9, v18, v74
	v_fmac_f32_e32 v9, v15, v75
	v_fmac_f32_e32 v9, v16, v73
	v_fmac_f32_e32 v9, v17, v72
	v_mul_f32_e32 v10, 0xbfb8aa3b, v9
	v_exp_f32_e32 v10, v10
	s_nop 0
	v_add_f32_e32 v10, 1.0, v10
	v_rcp_f32_e32 v10, v10
	s_nop 0
	v_mul_f32_e32 v9, v9, v10
	ds_write2_b32 v76, v8, v9 offset0:130 offset1:195
	v_mul_f32_e32 v8, v18, v73
	v_fmac_f32_e32 v8, v15, v74
	v_fmac_f32_e32 v8, v16, v72
	v_fmac_f32_e32 v8, v17, v71
	v_mul_f32_e32 v9, 0xbfb8aa3b, v8
	v_exp_f32_e32 v9, v9
	s_nop 0
	v_add_f32_e32 v9, 1.0, v9
	v_rcp_f32_e32 v9, v9
	s_nop 0
	v_mul_f32_e32 v8, v8, v9
	v_mul_f32_e32 v9, v18, v72
	v_fmac_f32_e32 v9, v15, v73
	v_fmac_f32_e32 v9, v16, v71
	v_fmac_f32_e32 v9, v17, v70
	v_mul_f32_e32 v10, 0xbfb8aa3b, v9
	v_exp_f32_e32 v10, v10
	s_nop 0
	v_add_f32_e32 v10, 1.0, v10
	v_rcp_f32_e32 v10, v10
	s_nop 0
	v_mul_f32_e32 v9, v9, v10
	v_add_u32_e32 v10, 0x400, v76
	ds_write2_b32 v10, v8, v9 offset0:4 offset1:69
	v_mul_f32_e32 v8, v18, v71
	v_fmac_f32_e32 v8, v15, v72
; __device__ __forceinline__ float siluf_(float x) { return x * sigmoidf_(x); }
; __device__ __forceinline__ void g1_phase(const PP P, int l, LAS unsigned char* lds) {
;     ...
;                     for (int i = 0; i < 32; ++i) { const float y = w0 * x0 + w1 * x1 + w2 * x2 + w3 * xv[i]; dst[(tb + i) * 65] = siluf_(y); x0 = x1; x1 = x2; x2 = xv[i]; } }
	v_fmac_f32_e32 v8, v16, v70
	v_fmac_f32_e32 v8, v17, v69
	v_mul_f32_e32 v9, 0xbfb8aa3b, v8
	v_exp_f32_e32 v9, v9
	s_nop 0
	v_add_f32_e32 v9, 1.0, v9
	v_rcp_f32_e32 v9, v9
	s_nop 0
	v_mul_f32_e32 v8, v8, v9
	v_mul_f32_e32 v9, v18, v70
	v_fmac_f32_e32 v9, v15, v71
	v_fmac_f32_e32 v9, v16, v69
	v_fmac_f32_e32 v9, v17, v63
	v_mul_f32_e32 v71, 0xbfb8aa3b, v9
	v_exp_f32_e32 v71, v71
	s_nop 0
	v_add_f32_e32 v71, 1.0, v71
	v_rcp_f32_e32 v71, v71
	s_nop 0
	v_mul_f32_e32 v9, v9, v71
	ds_write2_b32 v10, v8, v9 offset0:134 offset1:199
	v_mul_f32_e32 v8, v18, v69
	v_fmac_f32_e32 v8, v15, v70
	v_fmac_f32_e32 v8, v16, v63
	v_fmac_f32_e32 v8, v17, v61
	v_mul_f32_e32 v9, 0xbfb8aa3b, v8
	v_exp_f32_e32 v9, v9
	s_nop 0
	v_add_f32_e32 v9, 1.0, v9
	v_rcp_f32_e32 v9, v9
	s_nop 0
	v_mul_f32_e32 v8, v8, v9
	v_mul_f32_e32 v9, v18, v63
	v_fmac_f32_e32 v9, v15, v69
	v_fmac_f32_e32 v9, v16, v61
	v_fmac_f32_e32 v9, v17, v59
	v_mul_f32_e32 v10, 0xbfb8aa3b, v9
	v_exp_f32_e32 v10, v10
	s_nop 0
	v_add_f32_e32 v10, 1.0, v10
	v_rcp_f32_e32 v10, v10
	s_nop 0
	v_mul_f32_e32 v9, v9, v10
	v_add_u32_e32 v10, 0x800, v76
	ds_write2_b32 v10, v8, v9 offset0:8 offset1:73
	v_mul_f32_e32 v8, v18, v61
	v_fmac_f32_e32 v8, v15, v63
	v_fmac_f32_e32 v8, v16, v59
	v_fmac_f32_e32 v8, v17, v57
	v_mul_f32_e32 v9, 0xbfb8aa3b, v8
	v_exp_f32_e32 v9, v9
	s_nop 0
	v_add_f32_e32 v9, 1.0, v9
	v_rcp_f32_e32 v9, v9
	s_nop 0
	v_mul_f32_e32 v8, v8, v9
	v_mul_f32_e32 v9, v18, v59
	v_fmac_f32_e32 v9, v15, v61
	v_fmac_f32_e32 v9, v16, v57
	v_fmac_f32_e32 v9, v17, v55
	v_mul_f32_e32 v61, 0xbfb8aa3b, v9
	v_exp_f32_e32 v61, v61
	s_nop 0
	v_add_f32_e32 v61, 1.0, v61
	v_rcp_f32_e32 v61, v61
	s_nop 0
	v_mul_f32_e32 v9, v9, v61
	ds_write2_b32 v10, v8, v9 offset0:138 offset1:203
	v_mul_f32_e32 v8, v18, v57
	v_fmac_f32_e32 v8, v15, v59
	v_fmac_f32_e32 v8, v16, v55
	v_fmac_f32_e32 v8, v17, v53
	v_mul_f32_e32 v9, 0xbfb8aa3b, v8
	v_exp_f32_e32 v9, v9
	s_nop 0
	v_add_f32_e32 v9, 1.0, v9
	v_rcp_f32_e32 v9, v9
	s_nop 0
	v_mul_f32_e32 v8, v8, v9
	v_mul_f32_e32 v9, v18, v55
	v_fmac_f32_e32 v9, v15, v57
	v_fmac_f32_e32 v9, v16, v53
	v_fmac_f32_e32 v9, v17, v51
	v_mul_f32_e32 v10, 0xbfb8aa3b, v9
	v_exp_f32_e32 v10, v10
	s_nop 0
	v_add_f32_e32 v10, 1.0, v10
	v_rcp_f32_e32 v10, v10
	s_nop 0
	v_mul_f32_e32 v9, v9, v10
	v_add_u32_e32 v10, 0xc00, v76
	ds_write2_b32 v10, v8, v9 offset0:12 offset1:77
	v_mul_f32_e32 v8, v18, v53
	v_fmac_f32_e32 v8, v15, v55
	v_fmac_f32_e32 v8, v16, v51
	v_fmac_f32_e32 v8, v17, v49
	v_mul_f32_e32 v9, 0xbfb8aa3b, v8
	v_exp_f32_e32 v9, v9
	s_nop 0
	v_add_f32_e32 v9, 1.0, v9
	v_rcp_f32_e32 v9, v9
	s_nop 0
	v_mul_f32_e32 v8, v8, v9
	v_mul_f32_e32 v9, v18, v51
	v_fmac_f32_e32 v9, v15, v53
	v_fmac_f32_e32 v9, v16, v49
	v_fmac_f32_e32 v9, v17, v47
	v_mul_f32_e32 v53, 0xbfb8aa3b, v9
	v_exp_f32_e32 v53, v53
	s_nop 0
	v_add_f32_e32 v53, 1.0, v53
	v_rcp_f32_e32 v53, v53
	s_nop 0
	v_mul_f32_e32 v9, v9, v53
	ds_write2_b32 v10, v8, v9 offset0:142 offset1:207
	v_mul_f32_e32 v8, v18, v49
	v_fmac_f32_e32 v8, v15, v51
	v_fmac_f32_e32 v8, v16, v47
	v_fmac_f32_e32 v8, v17, v45
	v_mul_f32_e32 v9, 0xbfb8aa3b, v8
	v_exp_f32_e32 v9, v9
	s_nop 0
	v_add_f32_e32 v9, 1.0, v9
	v_rcp_f32_e32 v9, v9
	s_nop 0
	v_mul_f32_e32 v8, v8, v9
	v_mul_f32_e32 v9, v18, v47
	v_fmac_f32_e32 v9, v15, v49
	v_fmac_f32_e32 v9, v16, v45
	v_fmac_f32_e32 v9, v17, v43
	v_mul_f32_e32 v10, 0xbfb8aa3b, v9
	v_exp_f32_e32 v10, v10
	s_nop 0
	v_add_f32_e32 v10, 1.0, v10
	v_rcp_f32_e32 v10, v10
	s_nop 0
	v_mul_f32_e32 v9, v9, v10
	v_add_u32_e32 v10, 0x1000, v76
	ds_write2_b32 v10, v8, v9 offset0:16 offset1:81
	v_mul_f32_e32 v8, v18, v45
	v_fmac_f32_e32 v8, v15, v47
	v_fmac_f32_e32 v8, v16, v43
	v_fmac_f32_e32 v8, v17, v41
	v_mul_f32_e32 v9, 0xbfb8aa3b, v8
	v_exp_f32_e32 v9, v9
	s_nop 0
	v_add_f32_e32 v9, 1.0, v9
	v_rcp_f32_e32 v9, v9
	s_nop 0
	v_mul_f32_e32 v8, v8, v9
	v_mul_f32_e32 v9, v18, v43
	v_fmac_f32_e32 v9, v15, v45
	v_fmac_f32_e32 v9, v16, v41
; __device__ __forceinline__ float siluf_(float x) { return x * sigmoidf_(x); }
; __device__ __forceinline__ void g1_phase(const PP P, int l, LAS unsigned char* lds) {
;     ...
;                   for (int tb = 0; tb < 64; tb += 32) { float xv[32];
; #pragma unroll
;                     for (int i = 0; i < 32; ++i) { xv[i] = bf2f(*pr); pr += HLD; asm volatile("" : "+v"(pr)); }
; #pragma unroll
;                     for (int i = 0; i < 32; ++i) { const float y = w0 * x0 + w1 * x1 + w2 * x2 + w3 * xv[i]; dst[(tb + i) * 65] = siluf_(y); x0 = x1; x1 = x2; x2 = xv[i]; } }
	v_fmac_f32_e32 v9, v17, v39
	v_mul_f32_e32 v45, 0xbfb8aa3b, v9
	v_exp_f32_e32 v45, v45
	s_nop 0
	v_add_f32_e32 v45, 1.0, v45
	v_rcp_f32_e32 v45, v45
	s_nop 0
	v_mul_f32_e32 v9, v9, v45
	ds_write2_b32 v10, v8, v9 offset0:146 offset1:211
	v_mul_f32_e32 v8, v18, v41
	v_fmac_f32_e32 v8, v15, v43
	v_fmac_f32_e32 v8, v16, v39
	v_fmac_f32_e32 v8, v17, v37
	v_mul_f32_e32 v9, 0xbfb8aa3b, v8
	v_exp_f32_e32 v9, v9
	s_nop 0
	v_add_f32_e32 v9, 1.0, v9
	v_rcp_f32_e32 v9, v9
	s_nop 0
	v_mul_f32_e32 v8, v8, v9
	v_mul_f32_e32 v9, v18, v39
	v_fmac_f32_e32 v9, v15, v41
	v_fmac_f32_e32 v9, v16, v37
	v_fmac_f32_e32 v9, v17, v35
	v_mul_f32_e32 v10, 0xbfb8aa3b, v9
	v_exp_f32_e32 v10, v10
	s_nop 0
	v_add_f32_e32 v10, 1.0, v10
	v_rcp_f32_e32 v10, v10
	s_nop 0
	v_mul_f32_e32 v9, v9, v10
	v_add_u32_e32 v10, 0x1400, v76
	ds_write2_b32 v10, v8, v9 offset0:20 offset1:85
	v_mul_f32_e32 v8, v18, v37
	v_fmac_f32_e32 v8, v15, v39
	v_fmac_f32_e32 v8, v16, v35
	v_fmac_f32_e32 v8, v17, v23
	v_mul_f32_e32 v9, 0xbfb8aa3b, v8
	v_exp_f32_e32 v9, v9
	s_nop 0
	v_add_f32_e32 v9, 1.0, v9
	v_rcp_f32_e32 v9, v9
	s_nop 0
	v_mul_f32_e32 v8, v8, v9
	v_mul_f32_e32 v9, v18, v35
	v_fmac_f32_e32 v9, v15, v37
	v_fmac_f32_e32 v9, v16, v23
	v_fmac_f32_e32 v9, v17, v22
	v_mul_f32_e32 v37, 0xbfb8aa3b, v9
	v_exp_f32_e32 v37, v37
	s_nop 0
	v_add_f32_e32 v37, 1.0, v37
	v_rcp_f32_e32 v37, v37
	s_nop 0
	v_mul_f32_e32 v9, v9, v37
	ds_write2_b32 v10, v8, v9 offset0:150 offset1:215
	v_mul_f32_e32 v8, v18, v23
	v_fmac_f32_e32 v8, v15, v35
	v_fmac_f32_e32 v8, v16, v22
	v_fmac_f32_e32 v8, v17, v21
	v_mul_f32_e32 v9, 0xbfb8aa3b, v8
	v_exp_f32_e32 v9, v9
	s_nop 0
	v_add_f32_e32 v9, 1.0, v9
	v_rcp_f32_e32 v9, v9
	s_nop 0
	v_mul_f32_e32 v8, v8, v9
	v_mul_f32_e32 v9, v18, v22
	v_fmac_f32_e32 v9, v15, v23
	v_fmac_f32_e32 v9, v16, v21
	v_fmac_f32_e32 v9, v17, v20
	v_mul_f32_e32 v10, 0xbfb8aa3b, v9
	v_exp_f32_e32 v10, v10
	s_nop 0
	v_add_f32_e32 v10, 1.0, v10
	v_rcp_f32_e32 v10, v10
	s_nop 0
	v_mul_f32_e32 v9, v9, v10
	v_add_u32_e32 v10, 0x1800, v76
	ds_write2_b32 v10, v8, v9 offset0:24 offset1:89
	v_mul_f32_e32 v8, v18, v21
	v_fmac_f32_e32 v8, v15, v22
	v_fmac_f32_e32 v8, v16, v20
	v_fmac_f32_e32 v8, v17, v19
	v_mul_f32_e32 v9, 0xbfb8aa3b, v8
	v_exp_f32_e32 v9, v9
	s_nop 0
	v_add_f32_e32 v9, 1.0, v9
	v_rcp_f32_e32 v9, v9
	s_nop 0
	v_mul_f32_e32 v8, v8, v9
	v_mul_f32_e32 v9, v18, v20
	v_fmac_f32_e32 v9, v15, v21
	v_fmac_f32_e32 v9, v16, v19
	v_fmac_f32_e32 v9, v17, v7
	v_mul_f32_e32 v21, 0xbfb8aa3b, v9
	v_exp_f32_e32 v21, v21
	s_nop 0
	v_add_f32_e32 v21, 1.0, v21
	v_rcp_f32_e32 v21, v21
	s_nop 0
	v_mul_f32_e32 v9, v9, v21
	ds_write2_b32 v10, v8, v9 offset0:154 offset1:219
	v_mul_f32_e32 v8, v18, v19
	v_fmac_f32_e32 v8, v15, v20
	v_fmac_f32_e32 v8, v16, v7
	v_fmac_f32_e32 v8, v17, v6
	v_mul_f32_e32 v9, 0xbfb8aa3b, v8
	v_exp_f32_e32 v9, v9
	s_nop 0
	v_add_f32_e32 v9, 1.0, v9
	v_rcp_f32_e32 v9, v9
	s_nop 0
	v_mul_f32_e32 v8, v8, v9
	v_mul_f32_e32 v9, v18, v7
	v_fmac_f32_e32 v9, v15, v19
	v_fmac_f32_e32 v9, v16, v6
	v_fmac_f32_e32 v9, v17, v4
	v_mul_f32_e32 v10, 0xbfb8aa3b, v9
	v_exp_f32_e32 v10, v10
	s_nop 0
	v_add_f32_e32 v10, 1.0, v10
	v_rcp_f32_e32 v10, v10
	s_nop 0
	v_mul_f32_e32 v9, v9, v10
	v_add_u32_e32 v10, 0x1c00, v76
	ds_write2_b32 v10, v8, v9 offset0:28 offset1:93
	v_mul_f32_e32 v8, v18, v6
	v_fmac_f32_e32 v8, v15, v7
	v_fmac_f32_e32 v8, v16, v4
	v_fmac_f32_e32 v8, v17, v5
	v_mul_f32_e32 v7, 0xbfb8aa3b, v8
	v_exp_f32_e32 v7, v7
	s_nop 0
	v_add_f32_e32 v7, 1.0, v7
	v_rcp_f32_e32 v7, v7
	s_nop 0
	v_mul_f32_e32 v7, v8, v7
	v_mul_f32_e32 v8, v18, v4
	v_fmac_f32_e32 v8, v15, v6
	v_fmac_f32_e32 v8, v16, v5
	v_fmac_f32_e32 v8, v17, v11
	v_mul_f32_e32 v6, 0xbfb8aa3b, v8
	v_exp_f32_e32 v6, v6
	s_nop 0
	v_add_f32_e32 v6, 1.0, v6
	v_rcp_f32_e32 v6, v6
	s_nop 0
	v_mul_f32_e32 v6, v8, v6
	ds_write2_b32 v10, v7, v6 offset0:158 offset1:223
	v_mov_b32_e32 v10, v11
	v_mov_b64_e32 v[8:9], v[4:5]
	s_cbranch_vccz .LBB0_501

;     __device__ __forceinline__ void operator()(const f32x4 (&acc)[2][2][4][2], const pg8::Unit& u, int wr, int wc, int fr, int fq) const {
;     ...
;             if (mode == 3) {
; #pragma unroll
;                 for (int ai = 0; ai < 2; ++ai)
; #pragma unroll
;                     for (int m = 0; m < 4; ++m) { const int row = row0 + ai * 128 + m * 16;
;                         const float* src = (row < MP) ? xp + (size_t)row * 1024 : xs + (size_t)(row - MP) * 1024;
;                         float* dst = X + (size_t)row * 1024;
; #pragma unroll
;                         for (int bj = 0; bj < 2; ++bj)
; #pragma unroll
;                             for (int n = 0; n < 2; ++n) { const int col = u.pn * 256 + bj * 128 + wc * 32 + n * 16 + 4 * fq;
;                                 const f32x4 xi = *(const f32x4*)(src + col); f32x4 o = xi * DN_ALPHA + acc[ai][bj][m][n];
;                                 *(f32x4*)(dst + col) = o; }
;                         __builtin_amdgcn_sched_barrier(0); }
.LBB0_854:
	s_and_b64 vcc, exec, s[6:7]
	s_cbranch_vccz .LBB0_853
	v_cmp_lt_i32_e32 vcc, s93, v142
	s_and_saveexec_b64 s[6:7], vcc
	s_xor_b64 s[6:7], exec, s[6:7]
	v_add_u32_e32 v24, 0xffff8000, v142
	v_lshlrev_b64 v[144:145], 12, v[24:25]
	v_mov_b32_e32 v143, v25
	v_lshl_add_u64 v[146:147], s[56:57], 0, v[144:145]
	v_lshlrev_b64 v[148:149], 12, v[142:143]
	s_andn2_saveexec_b64 s[6:7], s[6:7]
	v_ashrrev_i32_e32 v143, 31, v142
	v_lshlrev_b64 v[148:149], 12, v[142:143]
	v_lshl_add_u64 v[146:147], s[2:3], 0, v[148:149]
	s_or_b64 exec, exec, s[6:7]
	v_or_b32_e32 v144, s15, v186
	v_ashrrev_i32_e32 v145, 31, v144
	v_lshlrev_b64 v[144:145], 2, v[144:145]
	v_lshl_add_u64 v[146:147], v[146:147], 0, v[144:145]
	v_lshl_add_u64 v[148:149], s[62:63], 0, v[148:149]
	v_lshl_add_u64 v[148:149], v[148:149], 0, v[144:145]
	s_mov_b64 s[6:7], 0x10000
	s_mov_b64 vcc, 0x40000
	global_load_dwordx4 v[190:193], v[146:147], off
	global_load_dwordx4 v[194:197], v[146:147], off offset:64
	global_load_dwordx4 v[198:201], v[146:147], off offset:512
	global_load_dwordx4 v[202:205], v[146:147], off offset:576
	v_lshl_add_u64 v[146:147], v[146:147], 0, s[6:7]
	global_load_dwordx4 v[206:209], v[146:147], off
	global_load_dwordx4 v[210:213], v[146:147], off offset:64
	global_load_dwordx4 v[214:217], v[146:147], off offset:512
	global_load_dwordx4 v[218:221], v[146:147], off offset:576
	v_lshl_add_u64 v[146:147], v[146:147], 0, s[6:7]
	global_load_dwordx4 v[222:225], v[146:147], off
	global_load_dwordx4 v[226:229], v[146:147], off offset:64
	global_load_dwordx4 v[230:233], v[146:147], off offset:512
	global_load_dwordx4 v[234:237], v[146:147], off offset:576
	v_lshl_add_u64 v[146:147], v[146:147], 0, s[6:7]
	global_load_dwordx4 v[238:241], v[146:147], off
	global_load_dwordx4 v[242:245], v[146:147], off offset:64
	global_load_dwordx4 v[246:249], v[146:147], off offset:512
	global_load_dwordx4 v[250:253], v[146:147], off offset:576
	v_lshl_add_u64 v[146:147], v[146:147], 0, s[6:7]
	v_lshl_add_u64 v[146:147], v[146:147], 0, vcc
	s_waitcnt vmcnt(15)
	v_pk_fma_f32 v[126:127], v[190:191], s[86:87], v[126:127] op_sel_hi:[1,0,1]
	v_pk_fma_f32 v[128:129], v[192:193], s[86:87], v[128:129] op_sel_hi:[1,0,1]
	s_waitcnt vmcnt(14)
	v_pk_fma_f32 v[122:123], v[194:195], s[86:87], v[122:123] op_sel_hi:[1,0,1]
	v_pk_fma_f32 v[124:125], v[196:197], s[86:87], v[124:125] op_sel_hi:[1,0,1]
	s_waitcnt vmcnt(13)
	v_pk_fma_f32 v[118:119], v[198:199], s[86:87], v[118:119] op_sel_hi:[1,0,1]
	v_pk_fma_f32 v[120:121], v[200:201], s[86:87], v[120:121] op_sel_hi:[1,0,1]
	s_waitcnt vmcnt(12)
	v_pk_fma_f32 v[114:115], v[202:203], s[86:87], v[114:115] op_sel_hi:[1,0,1]
	v_pk_fma_f32 v[116:117], v[204:205], s[86:87], v[116:117] op_sel_hi:[1,0,1]
	global_store_dwordx4 v[148:149], v[126:129], off
	global_store_dwordx4 v[148:149], v[122:125], off offset:64
	global_store_dwordx4 v[148:149], v[118:121], off offset:512
	global_store_dwordx4 v[148:149], v[114:117], off offset:576
	v_lshl_add_u64 v[148:149], v[148:149], 0, s[6:7]
	s_waitcnt vmcnt(15)
	v_pk_fma_f32 v[110:111], v[206:207], s[86:87], v[110:111] op_sel_hi:[1,0,1]
	v_pk_fma_f32 v[112:113], v[208:209], s[86:87], v[112:113] op_sel_hi:[1,0,1]
	s_waitcnt vmcnt(14)
	v_pk_fma_f32 v[106:107], v[210:211], s[86:87], v[106:107] op_sel_hi:[1,0,1]
	v_pk_fma_f32 v[108:109], v[212:213], s[86:87], v[108:109] op_sel_hi:[1,0,1]
	s_waitcnt vmcnt(13)
	v_pk_fma_f32 v[102:103], v[214:215], s[86:87], v[102:103] op_sel_hi:[1,0,1]
	v_pk_fma_f32 v[104:105], v[216:217], s[86:87], v[104:105] op_sel_hi:[1,0,1]
	s_waitcnt vmcnt(12)
	v_pk_fma_f32 v[98:99], v[218:219], s[86:87], v[98:99] op_sel_hi:[1,0,1]
	v_pk_fma_f32 v[100:101], v[220:221], s[86:87], v[100:101] op_sel_hi:[1,0,1]
	global_store_dwordx4 v[148:149], v[110:113], off
	global_store_dwordx4 v[148:149], v[106:109], off offset:64
	global_store_dwordx4 v[148:149], v[102:105], off offset:512
	global_store_dwordx4 v[148:149], v[98:101], off offset:576
	v_lshl_add_u64 v[148:149], v[148:149], 0, s[6:7]
	s_waitcnt vmcnt(15)
	v_pk_fma_f32 v[94:95], v[222:223], s[86:87], v[94:95] op_sel_hi:[1,0,1]
	v_pk_fma_f32 v[96:97], v[224:225], s[86:87], v[96:97] op_sel_hi:[1,0,1]
	s_waitcnt vmcnt(14)
	v_pk_fma_f32 v[90:91], v[226:227], s[86:87], v[90:91] op_sel_hi:[1,0,1]
	v_pk_fma_f32 v[92:93], v[228:229], s[86:87], v[92:93] op_sel_hi:[1,0,1]
	s_waitcnt vmcnt(13)
	v_pk_fma_f32 v[86:87], v[230:231], s[86:87], v[86:87] op_sel_hi:[1,0,1]
	v_pk_fma_f32 v[88:89], v[232:233], s[86:87], v[88:89] op_sel_hi:[1,0,1]
	s_waitcnt vmcnt(12)
	v_pk_fma_f32 v[82:83], v[234:235], s[86:87], v[82:83] op_sel_hi:[1,0,1]
	v_pk_fma_f32 v[84:85], v[236:237], s[86:87], v[84:85] op_sel_hi:[1,0,1]
	global_store_dwordx4 v[148:149], v[94:97], off
	global_store_dwordx4 v[148:149], v[90:93], off offset:64
	global_store_dwordx4 v[148:149], v[86:89], off offset:512
	global_store_dwordx4 v[148:149], v[82:85], off offset:576
	v_lshl_add_u64 v[148:149], v[148:149], 0, s[6:7]
	s_waitcnt vmcnt(15)
	v_pk_fma_f32 v[78:79], v[238:239], s[86:87], v[78:79] op_sel_hi:[1,0,1]
	v_pk_fma_f32 v[80:81], v[240:241], s[86:87], v[80:81] op_sel_hi:[1,0,1]
	s_waitcnt vmcnt(14)
	v_pk_fma_f32 v[74:75], v[242:243], s[86:87], v[74:75] op_sel_hi:[1,0,1]
	v_pk_fma_f32 v[76:77], v[244:245], s[86:87], v[76:77] op_sel_hi:[1,0,1]
	s_waitcnt vmcnt(13)
	v_pk_fma_f32 v[70:71], v[246:247], s[86:87], v[70:71] op_sel_hi:[1,0,1]
	v_pk_fma_f32 v[72:73], v[248:249], s[86:87], v[72:73] op_sel_hi:[1,0,1]
	s_waitcnt vmcnt(12)
;     __device__ __forceinline__ void operator()(const f32x4 (&acc)[2][2][4][2], const pg8::Unit& u, int wr, int wc, int fr, int fq) const {
;     ...
;             if (mode == 3) {
; #pragma unroll
;                 for (int ai = 0; ai < 2; ++ai)
; #pragma unroll
;                     for (int m = 0; m < 4; ++m) { const int row = row0 + ai * 128 + m * 16;
;                         const float* src = (row < MP) ? xp + (size_t)row * 1024 : xs + (size_t)(row - MP) * 1024;
;                         float* dst = X + (size_t)row * 1024;
; #pragma unroll
;                         for (int bj = 0; bj < 2; ++bj)
; #pragma unroll
;                             for (int n = 0; n < 2; ++n) { const int col = u.pn * 256 + bj * 128 + wc * 32 + n * 16 + 4 * fq;
;                                 const f32x4 xi = *(const f32x4*)(src + col); f32x4 o = xi * DN_ALPHA + acc[ai][bj][m][n];
;                                 *(f32x4*)(dst + col) = o; }
;                         __builtin_amdgcn_sched_barrier(0); }
	v_pk_fma_f32 v[66:67], v[250:251], s[86:87], v[66:67] op_sel_hi:[1,0,1]
	v_pk_fma_f32 v[68:69], v[252:253], s[86:87], v[68:69] op_sel_hi:[1,0,1]
	global_store_dwordx4 v[148:149], v[78:81], off
	global_store_dwordx4 v[148:149], v[74:77], off offset:64
	global_store_dwordx4 v[148:149], v[70:73], off offset:512
	global_store_dwordx4 v[148:149], v[66:69], off offset:576
	v_lshl_add_u64 v[148:149], v[148:149], 0, s[6:7]
	v_lshl_add_u64 v[148:149], v[148:149], 0, vcc
	global_load_dwordx4 v[190:193], v[146:147], off
	global_load_dwordx4 v[194:197], v[146:147], off offset:64
	global_load_dwordx4 v[198:201], v[146:147], off offset:512
	global_load_dwordx4 v[202:205], v[146:147], off offset:576
	v_lshl_add_u64 v[146:147], v[146:147], 0, s[6:7]
	global_load_dwordx4 v[206:209], v[146:147], off
	global_load_dwordx4 v[210:213], v[146:147], off offset:64
	global_load_dwordx4 v[214:217], v[146:147], off offset:512
	global_load_dwordx4 v[218:221], v[146:147], off offset:576
	v_lshl_add_u64 v[146:147], v[146:147], 0, s[6:7]
	global_load_dwordx4 v[222:225], v[146:147], off
	global_load_dwordx4 v[226:229], v[146:147], off offset:64
	global_load_dwordx4 v[230:233], v[146:147], off offset:512
	global_load_dwordx4 v[234:237], v[146:147], off offset:576
	v_lshl_add_u64 v[146:147], v[146:147], 0, s[6:7]
	global_load_dwordx4 v[238:241], v[146:147], off
	global_load_dwordx4 v[242:245], v[146:147], off offset:64
	global_load_dwordx4 v[246:249], v[146:147], off offset:512
	global_load_dwordx4 v[250:253], v[146:147], off offset:576
	v_lshl_add_u64 v[146:147], v[146:147], 0, s[6:7]
	s_waitcnt vmcnt(15)
	v_pk_fma_f32 v[62:63], v[190:191], s[86:87], v[62:63] op_sel_hi:[1,0,1]
	v_pk_fma_f32 v[64:65], v[192:193], s[86:87], v[64:65] op_sel_hi:[1,0,1]
	s_waitcnt vmcnt(14)
	v_pk_fma_f32 v[58:59], v[194:195], s[86:87], v[58:59] op_sel_hi:[1,0,1]
	v_pk_fma_f32 v[60:61], v[196:197], s[86:87], v[60:61] op_sel_hi:[1,0,1]
	s_waitcnt vmcnt(13)
	v_pk_fma_f32 v[54:55], v[198:199], s[86:87], v[54:55] op_sel_hi:[1,0,1]
	v_pk_fma_f32 v[56:57], v[200:201], s[86:87], v[56:57] op_sel_hi:[1,0,1]
	s_waitcnt vmcnt(12)
	v_pk_fma_f32 v[50:51], v[202:203], s[86:87], v[50:51] op_sel_hi:[1,0,1]
	v_pk_fma_f32 v[52:53], v[204:205], s[86:87], v[52:53] op_sel_hi:[1,0,1]
	global_store_dwordx4 v[148:149], v[62:65], off
	global_store_dwordx4 v[148:149], v[58:61], off offset:64
	global_store_dwordx4 v[148:149], v[54:57], off offset:512
	global_store_dwordx4 v[148:149], v[50:53], off offset:576
	v_lshl_add_u64 v[148:149], v[148:149], 0, s[6:7]
	s_waitcnt vmcnt(15)
	v_pk_fma_f32 v[46:47], v[206:207], s[86:87], v[46:47] op_sel_hi:[1,0,1]
	v_pk_fma_f32 v[48:49], v[208:209], s[86:87], v[48:49] op_sel_hi:[1,0,1]
	s_waitcnt vmcnt(14)
	v_pk_fma_f32 v[42:43], v[210:211], s[86:87], v[42:43] op_sel_hi:[1,0,1]
	v_pk_fma_f32 v[44:45], v[212:213], s[86:87], v[44:45] op_sel_hi:[1,0,1]
	s_waitcnt vmcnt(13)
	v_pk_fma_f32 v[38:39], v[214:215], s[86:87], v[38:39] op_sel_hi:[1,0,1]
	v_pk_fma_f32 v[40:41], v[216:217], s[86:87], v[40:41] op_sel_hi:[1,0,1]
	s_waitcnt vmcnt(12)
	v_pk_fma_f32 v[34:35], v[218:219], s[86:87], v[34:35] op_sel_hi:[1,0,1]
	v_pk_fma_f32 v[36:37], v[220:221], s[86:87], v[36:37] op_sel_hi:[1,0,1]
	global_store_dwordx4 v[148:149], v[46:49], off
	global_store_dwordx4 v[148:149], v[42:45], off offset:64
	global_store_dwordx4 v[148:149], v[38:41], off offset:512
	global_store_dwordx4 v[148:149], v[34:37], off offset:576
	v_lshl_add_u64 v[148:149], v[148:149], 0, s[6:7]
	s_waitcnt vmcnt(15)
	v_pk_fma_f32 v[30:31], v[222:223], s[86:87], v[30:31] op_sel_hi:[1,0,1]
	v_pk_fma_f32 v[32:33], v[224:225], s[86:87], v[32:33] op_sel_hi:[1,0,1]
	s_waitcnt vmcnt(14)
	v_pk_fma_f32 v[26:27], v[226:227], s[86:87], v[26:27] op_sel_hi:[1,0,1]
	v_pk_fma_f32 v[28:29], v[228:229], s[86:87], v[28:29] op_sel_hi:[1,0,1]
	s_waitcnt vmcnt(13)
	v_pk_fma_f32 v[20:21], v[230:231], s[86:87], v[20:21] op_sel_hi:[1,0,1]
	v_pk_fma_f32 v[22:23], v[232:233], s[86:87], v[22:23] op_sel_hi:[1,0,1]
	s_waitcnt vmcnt(12)
	v_pk_fma_f32 v[16:17], v[234:235], s[86:87], v[16:17] op_sel_hi:[1,0,1]
	v_pk_fma_f32 v[18:19], v[236:237], s[86:87], v[18:19] op_sel_hi:[1,0,1]
	global_store_dwordx4 v[148:149], v[30:33], off
	global_store_dwordx4 v[148:149], v[26:29], off offset:64
	global_store_dwordx4 v[148:149], v[20:23], off offset:512
	global_store_dwordx4 v[148:149], v[16:19], off offset:576
	v_lshl_add_u64 v[148:149], v[148:149], 0, s[6:7]
	s_waitcnt vmcnt(15)
	v_pk_fma_f32 v[12:13], v[238:239], s[86:87], v[12:13] op_sel_hi:[1,0,1]
	v_pk_fma_f32 v[14:15], v[240:241], s[86:87], v[14:15] op_sel_hi:[1,0,1]
	s_waitcnt vmcnt(14)
	v_pk_fma_f32 v[8:9], v[242:243], s[86:87], v[8:9] op_sel_hi:[1,0,1]
	v_pk_fma_f32 v[10:11], v[244:245], s[86:87], v[10:11] op_sel_hi:[1,0,1]
	s_waitcnt vmcnt(13)
	v_pk_fma_f32 v[4:5], v[246:247], s[86:87], v[4:5] op_sel_hi:[1,0,1]
	v_pk_fma_f32 v[6:7], v[248:249], s[86:87], v[6:7] op_sel_hi:[1,0,1]
	s_waitcnt vmcnt(12)
	v_pk_fma_f32 v[0:1], v[250:251], s[86:87], v[0:1] op_sel_hi:[1,0,1]
	v_pk_fma_f32 v[2:3], v[252:253], s[86:87], v[2:3] op_sel_hi:[1,0,1]
	global_store_dwordx4 v[148:149], v[12:15], off
	global_store_dwordx4 v[148:149], v[8:11], off offset:64
	global_store_dwordx4 v[148:149], v[4:7], off offset:512
	global_store_dwordx4 v[148:149], v[0:3], off offset:576
	v_lshl_add_u64 v[148:149], v[148:149], 0, s[6:7]
	s_and_b64 vcc, exec, s[4:5]
	s_mov_b64 s[4:5], -1
	s_cbranch_vccnz .LBB0_804
